# k25
# speedup vs baseline: 1.0366x; 1.0024x over previous
; DI float bf2f(bf16_t b) { return __uint_as_float(((unsigned)b) << 16); }
; DI bf16_t f2bf(float x) { return (bf16_t)(pk2(x, 0.f) & 0xffffu); }
; DI void run_phase(unsigned char* smem_in, const Params& P, int ph) {
;     ...
;     for (int it = bid; it < 272 + 512; it += nb) {
;       if (it < 256) {
;         const int idx = it * 256 + tid, e = idx & 4095, hd = (idx >> 12) & 3, b = idx >> 14, dk = e & 63;
;         bf16_t* S = (bf16_t*)(ws + OFF_HGS); const float* dec = (const float*)(ws + OFF_HGD);
;         float run = 0.f;
; #pragma unroll 1
;         for (int c0 = 0; c0 < 128; c0 += 16) {
;           float u[16], d[16];
; #pragma unroll
;           for (int j = 0; j < 16; ++j) { const int ch = b * 128 + c0 + j; u[j] = bf2f(S[((size_t)ch * 4 + hd) * 4096 + e]); d[j] = dec[(size_t)ch * 256 + hd * 64 + dk]; }
; #pragma unroll
;           for (int j = 0; j < 16; ++j) { const int ch = b * 128 + c0 + j; S[((size_t)ch * 4 + hd) * 4096 + e] = f2bf(run); run = d[j] * run + u[j]; }
;         }
;       } else if (it < 272) {
;         const int idx = (it - 256) * 256 + tid, n = idx & 63, b = (idx >> 6) & 3, g = idx >> 8;
.LBB0_472:
	s_cmpk_gt_i32 s84, 0xff
	s_mov_b64 s[0:1], -1
	s_cbranch_scc0 .LBB0_537
	s_cmpk_gt_u32 s84, 0x13f
	s_cbranch_scc0 .LBB0_533
.Lattn_entry_0:
	s_cmp_eq_u32 s9, 0
	s_cbranch_scc1 .Lstag_in_0
	s_barrier

; DI void run_phase(unsigned char* smem_in, const Params& P, int ph) {
;     ...
;       } else if (it < 272) {
;         const int idx = (it - 256) * 256 + tid, n = idx & 63, b = (idx >> 6) & 3, g = idx >> 8;
;         const float* al = (const float*)(ws + OFF_S5AL) + (size_t)((l * 16 + g) * 64 + n) * 2;
;         const float ar = al[0], ai = al[1];
;         const float* E = (const float*)(ws + OFF_S5E); bf16_t* A = (bf16_t*)(ws + OFF_S5A);
;         float hr = 0.f, hi = 0.f;
; #pragma unroll 1
;         for (int c0 = 0; c0 < 256; c0 += 16) {
;           float er[16], ei[16];
; #pragma unroll
;           for (int j = 0; j < 16; ++j) { const size_t row = (size_t)g * 1024 + b * 256 + c0 + j; er[j] = E[row * 128 + n]; ei[j] = E[row * 128 + 64 + n]; }
.LBB0_533:
	s_and_b64 vcc, exec, s[0:1]
	s_cbranch_vccz .LBB0_536
	v_cmp_gt_u32_e32 vcc, 64, v205
	s_and_saveexec_b64 s[100:101], vcc
	s_cbranch_execz .Ls5_skip_0
	s_sub_i32 s98, s84, 0x100
	s_lshr_b32 s99, s98, 2
	s_and_b32 s98, s98, 3
	v_mov_b32_e32 v8, s99
	v_lshl_or_b32 v4, v8, 6, v207
	v_ashrrev_i32_e32 v5, 31, v4
	v_lshl_add_u64 v[4:5], v[4:5], 3, s[38:39]
	global_load_dwordx2 v[4:5], v[4:5], off
	s_mov_b32 s0, 0x140000
	v_ashrrev_i32_e32 v9, 31, v8
	v_mov_b32_e32 v16, 0
	v_mad_i64_i32 v[6:7], s[0:1], v8, s0, v[190:191]
	v_lshlrev_b64 v[8:9], 19, v[8:9]
	s_mov_b32 s2, -16
	v_lshl_add_u64 v[8:9], v[192:193], 0, v[8:9]
	s_mul_i32 s99, s98, 0x50000
	s_lshl_b32 s98, s98, 17
	v_add_co_u32_e32 v6, vcc, s99, v6
	s_nop 1
	v_addc_co_u32_e32 v7, vcc, 0, v7, vcc
	v_add_co_u32_e32 v8, vcc, s98, v8
	s_nop 1
	v_addc_co_u32_e32 v9, vcc, 0, v9, vcc
	v_mov_b32_e32 v17, v16
	s_waitcnt vmcnt(0)
	v_pk_mov_b32 v[10:11], v[4:5], v[4:5] op_sel:[1,0]

; DI void run_phase(unsigned char* smem_in, const Params& P, int ph) {
;     ...
;       } else {
;         const int i = it - 272, x = (i >> 1) & 7, bh = x * 2 + (i & 1), j = i >> 4;
;         for (int rep = 0; rep < ATTN_REPS; ++rep) {
;           attn_unit(smem, P, bh, 63 - j);
;           attn_unit(smem, P, bh, j);
;         }
.Ls5_skip_0:
	s_or_b64 exec, exec, s[100:101]
	s_cmpk_gt_u32 s84, 0x10f
	s_cbranch_scc1 .Lattn_entry_0

; DI float bf2f(bf16_t b) { return __uint_as_float(((unsigned)b) << 16); }
; DI bf16_t f2bf(float x) { return (bf16_t)(pk2(x, 0.f) & 0xffffu); }
; DI void run_phase(unsigned char* smem_in, const Params& P, int ph) {
;     ...
;     for (int it = bid; it < 272 + 512; it += nb) {
;       if (it < 256) {
;         const int idx = it * 256 + tid, e = idx & 4095, hd = (idx >> 12) & 3, b = idx >> 14, dk = e & 63;
;         bf16_t* S = (bf16_t*)(ws + OFF_HGS); const float* dec = (const float*)(ws + OFF_HGD);
;         float run = 0.f;
; #pragma unroll 1
;         for (int c0 = 0; c0 < 128; c0 += 16) {
;           float u[16], d[16];
; #pragma unroll
;           for (int j = 0; j < 16; ++j) { const int ch = b * 128 + c0 + j; u[j] = bf2f(S[((size_t)ch * 4 + hd) * 4096 + e]); d[j] = dec[(size_t)ch * 256 + hd * 64 + dk]; }
; #pragma unroll
;           for (int j = 0; j < 16; ++j) { const int ch = b * 128 + c0 + j; S[((size_t)ch * 4 + hd) * 4096 + e] = f2bf(run); run = d[j] * run + u[j]; }
;         }
;       } else if (it < 272) {
;         const int idx = (it - 256) * 256 + tid, n = idx & 63, b = (idx >> 6) & 3, g = idx >> 8;
.LBB0_1393:
	s_cmpk_gt_i32 s85, 0xff
	s_mov_b64 s[0:1], -1
	s_cbranch_scc0 .LBB0_1458
	s_cmpk_gt_u32 s85, 0x13f
	s_cbranch_scc0 .LBB0_1454

; DI void run_phase(unsigned char* smem_in, const Params& P, int ph) {
;     ...
;       } else if (it < 272) {
;         const int idx = (it - 256) * 256 + tid, n = idx & 63, b = (idx >> 6) & 3, g = idx >> 8;
;         const float* al = (const float*)(ws + OFF_S5AL) + (size_t)((l * 16 + g) * 64 + n) * 2;
;         const float ar = al[0], ai = al[1];
;         const float* E = (const float*)(ws + OFF_S5E); bf16_t* A = (bf16_t*)(ws + OFF_S5A);
;         float hr = 0.f, hi = 0.f;
; #pragma unroll 1
;         for (int c0 = 0; c0 < 256; c0 += 16) {
;           float er[16], ei[16];
; #pragma unroll
;           for (int j = 0; j < 16; ++j) { const size_t row = (size_t)g * 1024 + b * 256 + c0 + j; er[j] = E[row * 128 + n]; ei[j] = E[row * 128 + 64 + n]; }
.LBB0_1454:
	s_and_b64 vcc, exec, s[0:1]
	s_cbranch_vccz .LBB0_1457
	v_cmp_gt_u32_e32 vcc, 64, v205
	s_and_saveexec_b64 s[100:101], vcc
	s_cbranch_execz .Ls5_skip_1
	s_sub_i32 s98, s85, 0x100
	s_lshr_b32 s99, s98, 2
	s_and_b32 s98, s98, 3
	v_mov_b32_e32 v8, s99
	v_lshl_add_u32 v4, v8, 6, v207
	v_ashrrev_i32_e32 v5, 31, v4
	v_lshl_add_u64 v[4:5], v[4:5], 3, s[38:39]
	global_load_dwordx2 v[4:5], v[4:5], off
	s_mov_b32 s0, 0x140000
	v_ashrrev_i32_e32 v9, 31, v8
	v_mov_b32_e32 v16, 0
	v_mad_i64_i32 v[6:7], s[0:1], v8, s0, v[190:191]
	v_lshlrev_b64 v[8:9], 19, v[8:9]
	s_mov_b32 s2, -16
	v_lshl_add_u64 v[8:9], v[192:193], 0, v[8:9]
	s_mul_i32 s99, s98, 0x50000
	s_lshl_b32 s98, s98, 17
	v_add_co_u32_e32 v6, vcc, s99, v6
	s_nop 1
	v_addc_co_u32_e32 v7, vcc, 0, v7, vcc
	v_add_co_u32_e32 v8, vcc, s98, v8
	s_nop 1
	v_addc_co_u32_e32 v9, vcc, 0, v9, vcc
	v_mov_b32_e32 v17, v16
	s_waitcnt vmcnt(0)
	v_pk_mov_b32 v[10:11], v[4:5], v[4:5] op_sel:[1,0]

; DI void run_phase(unsigned char* smem_in, const Params& P, int ph) {
;     ...
;       } else {
;         const int i = it - 272, x = (i >> 1) & 7, bh = x * 2 + (i & 1), j = i >> 4;
;         for (int rep = 0; rep < ATTN_REPS; ++rep) {
;           attn_unit(smem, P, bh, 63 - j);
;           attn_unit(smem, P, bh, j);
;         }
.Ls5_skip_1:
	s_or_b64 exec, exec, s[100:101]
	s_cmpk_gt_u32 s85, 0x10f
	s_cbranch_scc1 .Lattn_entry_1
